# acc zeroing replaced by C=0 half-iteration peel in all 4 GEMM phases; P5/P6 unit-boundary vmcnt drains relaxed
# speedup vs baseline: 1.0160x; 1.0102x over previous
.LBB0_161:
	s_ashr_i32 s79, s78, 31
	s_lshl_b64 s[70:71], s[78:79], 19
	s_add_u32 s80, s34, s70
	s_addc_u32 s81, s35, s71
	s_and_b64 s[70:71], s[2:3], exec
	s_cselect_b32 s79, s81, s87
	s_cselect_b32 vcc_lo, s80, s86
	s_ashr_i32 s13, s12, 31
	s_lshl_b64 s[70:71], s[12:13], 19
	s_add_u32 s82, s4, s70
	s_addc_u32 s83, s5, s71
	s_and_b64 s[70:71], s[2:3], exec
	s_cselect_b32 s13, s83, s89
	s_cselect_b32 vcc_hi, s82, s88
	s_add_u32 s86, s86, 0x40080
	s_addc_u32 s87, s87, 0
	s_add_u32 s70, s88, 0x100
	s_addc_u32 s71, s89, 0
	s_mov_b32 s72, -2
	ds_read_b128 v[144:147], v151
	ds_read_b128 v[154:157], v151 offset:1024
	ds_read_b128 v[158:161], v151 offset:2048
	ds_read_b128 v[162:165], v151 offset:3072
	ds_read_b128 v[170:173], v152
	ds_read_b128 v[174:177], v152 offset:1024
	ds_read_b128 v[178:181], v152 offset:2048
	ds_read_b128 v[182:185], v152 offset:3072
	s_add_u32 s0, s86, 0xfffc0080
	s_addc_u32 s1, s87, -1
	s_cmp_eq_u32 s72, 12
	s_cselect_b32 s91, s79, s1
	s_cselect_b32 s90, vcc_lo, s0
	s_cselect_b32 s89, s13, s71
	s_cselect_b32 s88, vcc_hi, s70
	v_lshl_add_u64 v[166:167], s[86:87], 0, v[136:137]
	s_add_i32 m0, s85, 0xc000
	ds_read_b128 v[194:197], v153
	ds_read_b128 v[198:201], v153 offset:1024
	ds_read_b128 v[202:205], v153 offset:2048
	ds_read_b128 v[206:209], v153 offset:3072
	ds_read_b128 v[210:213], v153 offset:4096
	ds_read_b128 v[214:217], v153 offset:5120
	ds_read_b128 v[218:221], v153 offset:6144
	ds_read_b128 v[222:225], v153 offset:7168
	global_load_lds_dwordx4 v[166:167], off
	v_lshl_add_u64 v[166:167], s[86:87], 0, v[138:139]
	s_add_i32 m0, s85, 0xe000
	s_nop 0
	global_load_lds_dwordx4 v[166:167], off
	s_waitcnt vmcnt(8)
	s_waitcnt lgkmcnt(0)
	s_barrier
	s_setprio 1
	s_waitcnt lgkmcnt(0)
	v_mfma_f32_16x16x32_bf16 v[124:127], v[144:147], v[194:197], 0
	v_mfma_f32_16x16x32_bf16 v[120:123], v[158:161], v[194:197], 0
	v_mfma_f32_16x16x32_bf16 v[116:119], v[144:147], v[202:205], 0
	v_mfma_f32_16x16x32_bf16 v[108:111], v[158:161], v[202:205], 0
	v_mfma_f32_16x16x32_bf16 v[100:103], v[144:147], v[210:213], 0
	v_mfma_f32_16x16x32_bf16 v[92:95], v[158:161], v[210:213], 0
	v_mfma_f32_16x16x32_bf16 v[84:87], v[144:147], v[218:221], 0
	v_mfma_f32_16x16x32_bf16 v[76:79], v[158:161], v[218:221], 0
	v_mfma_f32_16x16x32_bf16 v[124:127], v[154:157], v[198:201], v[124:127]
	v_mfma_f32_16x16x32_bf16 v[120:123], v[162:165], v[198:201], v[120:123]
	v_mfma_f32_16x16x32_bf16 v[116:119], v[154:157], v[206:209], v[116:119]
	v_mfma_f32_16x16x32_bf16 v[108:111], v[162:165], v[206:209], v[108:111]
	v_mfma_f32_16x16x32_bf16 v[100:103], v[154:157], v[214:217], v[100:103]
	v_mfma_f32_16x16x32_bf16 v[92:95], v[162:165], v[214:217], v[92:95]
	v_mfma_f32_16x16x32_bf16 v[84:87], v[154:157], v[222:225], v[84:87]
	v_mfma_f32_16x16x32_bf16 v[76:79], v[162:165], v[222:225], v[76:79]
	s_setprio 0
	s_setprio 1
	v_mfma_f32_16x16x32_bf16 v[112:115], v[170:173], v[194:197], 0
	v_mfma_f32_16x16x32_bf16 v[104:107], v[178:181], v[194:197], 0
	v_mfma_f32_16x16x32_bf16 v[96:99], v[170:173], v[202:205], 0
	v_mfma_f32_16x16x32_bf16 v[88:91], v[178:181], v[202:205], 0
	v_mfma_f32_16x16x32_bf16 v[80:83], v[170:173], v[210:213], 0
	v_mfma_f32_16x16x32_bf16 v[72:75], v[178:181], v[210:213], 0
	v_mfma_f32_16x16x32_bf16 v[68:71], v[170:173], v[218:221], 0
	v_mfma_f32_16x16x32_bf16 v[64:67], v[178:181], v[218:221], 0
	v_mfma_f32_16x16x32_bf16 v[112:115], v[174:177], v[198:201], v[112:115]
	v_mfma_f32_16x16x32_bf16 v[104:107], v[182:185], v[198:201], v[104:107]
	v_mfma_f32_16x16x32_bf16 v[96:99], v[174:177], v[206:209], v[96:99]
	v_mfma_f32_16x16x32_bf16 v[88:91], v[182:185], v[206:209], v[88:91]
	v_mfma_f32_16x16x32_bf16 v[80:83], v[174:177], v[214:217], v[80:83]
	v_mfma_f32_16x16x32_bf16 v[72:75], v[182:185], v[214:217], v[72:75]
	v_mfma_f32_16x16x32_bf16 v[68:71], v[174:177], v[222:225], v[68:71]
	v_mfma_f32_16x16x32_bf16 v[64:67], v[182:185], v[222:225], v[64:67]
	s_setprio 0
	s_barrier
	s_add_i32 s0, s18, s75
	v_lshl_add_u64 v[166:167], s[88:89], 0, v[130:131]
	s_mov_b32 m0, s0
	ds_read_b128 v[194:197], v153 offset:16384
	ds_read_b128 v[198:201], v153 offset:17408
	ds_read_b128 v[202:205], v153 offset:18432
	ds_read_b128 v[206:209], v153 offset:19456
	ds_read_b128 v[210:213], v153 offset:20480
	ds_read_b128 v[214:217], v153 offset:21504
	ds_read_b128 v[218:221], v153 offset:22528
	ds_read_b128 v[222:225], v153 offset:23552
	global_load_lds_dwordx4 v[166:167], off
	s_add_i32 m0, s0, 0x2000
	s_add_u32 s0, s88, 0x40000
	v_lshl_add_u64 v[168:169], s[88:89], 0, v[134:135]
	s_addc_u32 s1, s89, 0
	s_add_i32 s73, s19, s75
	global_load_lds_dwordx4 v[168:169], off
	v_lshl_add_u64 v[186:187], s[0:1], 0, v[130:131]
	s_mov_b32 m0, s73
	v_lshl_add_u64 v[190:191], s[90:91], 0, v[132:133]
	global_load_lds_dwordx4 v[186:187], off
	v_lshl_add_u64 v[186:187], s[0:1], 0, v[134:135]
	s_add_i32 m0, s73, 0x2000
	s_nop 0
	global_load_lds_dwordx4 v[186:187], off
	v_lshl_add_u64 v[186:187], s[90:91], 0, v[128:129]
	s_mov_b32 m0, s85
	s_nop 0
	global_load_lds_dwordx4 v[186:187], off
	s_mov_b32 m0, s76
	s_nop 0
	global_load_lds_dwordx4 v[190:191], off
	s_waitcnt vmcnt(8)
	s_waitcnt lgkmcnt(0)
	s_barrier
	s_setprio 1
	s_waitcnt lgkmcnt(0)
	v_mfma_f32_16x16x32_bf16 v[60:63], v[144:147], v[194:197], 0
	v_mfma_f32_16x16x32_bf16 v[56:59], v[158:161], v[194:197], 0
	v_mfma_f32_16x16x32_bf16 v[52:55], v[144:147], v[202:205], 0
	v_mfma_f32_16x16x32_bf16 v[44:47], v[158:161], v[202:205], 0
	v_mfma_f32_16x16x32_bf16 v[36:39], v[144:147], v[210:213], 0
	v_mfma_f32_16x16x32_bf16 v[28:31], v[158:161], v[210:213], 0
	v_mfma_f32_16x16x32_bf16 v[20:23], v[144:147], v[218:221], 0
	v_mfma_f32_16x16x32_bf16 v[12:15], v[158:161], v[218:221], 0
	v_mfma_f32_16x16x32_bf16 v[60:63], v[154:157], v[198:201], v[60:63]
	v_mfma_f32_16x16x32_bf16 v[56:59], v[162:165], v[198:201], v[56:59]
	v_mfma_f32_16x16x32_bf16 v[52:55], v[154:157], v[206:209], v[52:55]
	v_mfma_f32_16x16x32_bf16 v[44:47], v[162:165], v[206:209], v[44:47]
	v_mfma_f32_16x16x32_bf16 v[36:39], v[154:157], v[214:217], v[36:39]
	v_mfma_f32_16x16x32_bf16 v[28:31], v[162:165], v[214:217], v[28:31]
	v_mfma_f32_16x16x32_bf16 v[20:23], v[154:157], v[222:225], v[20:23]
	v_mfma_f32_16x16x32_bf16 v[12:15], v[162:165], v[222:225], v[12:15]
	s_setprio 0
	s_setprio 1
	v_mfma_f32_16x16x32_bf16 v[48:51], v[170:173], v[194:197], 0
	v_mfma_f32_16x16x32_bf16 v[40:43], v[178:181], v[194:197], 0
	v_mfma_f32_16x16x32_bf16 v[32:35], v[170:173], v[202:205], 0
	v_mfma_f32_16x16x32_bf16 v[24:27], v[178:181], v[202:205], 0
	v_mfma_f32_16x16x32_bf16 v[16:19], v[170:173], v[210:213], 0
	v_mfma_f32_16x16x32_bf16 v[8:11], v[178:181], v[210:213], 0
	v_mfma_f32_16x16x32_bf16 v[4:7], v[170:173], v[218:221], 0
	v_mfma_f32_16x16x32_bf16 v[0:3], v[178:181], v[218:221], 0
	v_mfma_f32_16x16x32_bf16 v[48:51], v[174:177], v[198:201], v[48:51]
	v_mfma_f32_16x16x32_bf16 v[40:43], v[182:185], v[198:201], v[40:43]
	v_mfma_f32_16x16x32_bf16 v[32:35], v[174:177], v[206:209], v[32:35]
	v_mfma_f32_16x16x32_bf16 v[24:27], v[182:185], v[206:209], v[24:27]
	v_mfma_f32_16x16x32_bf16 v[16:19], v[174:177], v[214:217], v[16:19]
	v_mfma_f32_16x16x32_bf16 v[8:11], v[182:185], v[214:217], v[8:11]
	v_mfma_f32_16x16x32_bf16 v[4:7], v[174:177], v[222:225], v[4:7]
	v_mfma_f32_16x16x32_bf16 v[0:3], v[182:185], v[222:225], v[0:3]
	s_setprio 0
	s_barrier
	s_branch .Lpeelp1_mid

.Lpeelp1_mid:
	s_add_i32 s73, 0, 0x18000
	s_add_i32 s16, 0, 0x1c000
	v_add_u32_e32 v162, s73, v149
	v_add_u32_e32 v182, s16, v149
	ds_read_b128 v[144:147], v162
	ds_read_b128 v[154:157], v162 offset:1024
	ds_read_b128 v[158:161], v162 offset:2048
	ds_read_b128 v[162:165], v162 offset:3072
	ds_read_b128 v[170:173], v182
	ds_read_b128 v[174:177], v182 offset:1024
	ds_read_b128 v[178:181], v182 offset:2048
	ds_read_b128 v[182:185], v182 offset:3072
	s_add_u32 s0, s90, 0x40000
	s_addc_u32 s1, s91, 0
	s_mov_b32 m0, s77
	v_lshl_add_u64 v[192:193], s[0:1], 0, v[128:129]
	ds_read_b128 v[194:197], v153 offset:32768
	ds_read_b128 v[198:201], v153 offset:33792
	ds_read_b128 v[202:205], v153 offset:34816
	ds_read_b128 v[206:209], v153 offset:35840
	ds_read_b128 v[210:213], v153 offset:36864
	ds_read_b128 v[214:217], v153 offset:37888
	ds_read_b128 v[218:221], v153 offset:38912
	ds_read_b128 v[222:225], v153 offset:39936
	global_load_lds_dwordx4 v[192:193], off
	v_lshl_add_u64 v[192:193], s[0:1], 0, v[132:133]
	s_mov_b32 m0, s68
	s_nop 0
	global_load_lds_dwordx4 v[192:193], off
	s_waitcnt vmcnt(8)
	s_waitcnt lgkmcnt(0)
	s_barrier
	s_setprio 1
	s_waitcnt lgkmcnt(0)
	v_mfma_f32_16x16x32_bf16 v[124:127], v[144:147], v[194:197], v[124:127]
	v_mfma_f32_16x16x32_bf16 v[120:123], v[158:161], v[194:197], v[120:123]
	v_mfma_f32_16x16x32_bf16 v[116:119], v[144:147], v[202:205], v[116:119]
	v_mfma_f32_16x16x32_bf16 v[108:111], v[158:161], v[202:205], v[108:111]
	v_mfma_f32_16x16x32_bf16 v[100:103], v[144:147], v[210:213], v[100:103]
	v_mfma_f32_16x16x32_bf16 v[92:95], v[158:161], v[210:213], v[92:95]
	v_mfma_f32_16x16x32_bf16 v[84:87], v[144:147], v[218:221], v[84:87]
	v_mfma_f32_16x16x32_bf16 v[76:79], v[158:161], v[218:221], v[76:79]
	v_mfma_f32_16x16x32_bf16 v[124:127], v[154:157], v[198:201], v[124:127]
	v_mfma_f32_16x16x32_bf16 v[120:123], v[162:165], v[198:201], v[120:123]
	v_mfma_f32_16x16x32_bf16 v[116:119], v[154:157], v[206:209], v[116:119]
	v_mfma_f32_16x16x32_bf16 v[108:111], v[162:165], v[206:209], v[108:111]
	v_mfma_f32_16x16x32_bf16 v[100:103], v[154:157], v[214:217], v[100:103]
	v_mfma_f32_16x16x32_bf16 v[92:95], v[162:165], v[214:217], v[92:95]
	v_mfma_f32_16x16x32_bf16 v[84:87], v[154:157], v[222:225], v[84:87]
	v_mfma_f32_16x16x32_bf16 v[76:79], v[162:165], v[222:225], v[76:79]
	s_setprio 0
	s_setprio 1
	v_mfma_f32_16x16x32_bf16 v[112:115], v[170:173], v[194:197], v[112:115]
	v_mfma_f32_16x16x32_bf16 v[104:107], v[178:181], v[194:197], v[104:107]
	v_mfma_f32_16x16x32_bf16 v[96:99], v[170:173], v[202:205], v[96:99]
	v_mfma_f32_16x16x32_bf16 v[88:91], v[178:181], v[202:205], v[88:91]
	v_mfma_f32_16x16x32_bf16 v[80:83], v[170:173], v[210:213], v[80:83]
	v_mfma_f32_16x16x32_bf16 v[72:75], v[178:181], v[210:213], v[72:75]
	v_mfma_f32_16x16x32_bf16 v[68:71], v[170:173], v[218:221], v[68:71]
	v_mfma_f32_16x16x32_bf16 v[64:67], v[178:181], v[218:221], v[64:67]
	v_mfma_f32_16x16x32_bf16 v[112:115], v[174:177], v[198:201], v[112:115]
	v_mfma_f32_16x16x32_bf16 v[104:107], v[182:185], v[198:201], v[104:107]
	v_mfma_f32_16x16x32_bf16 v[96:99], v[174:177], v[206:209], v[96:99]
	v_mfma_f32_16x16x32_bf16 v[88:91], v[182:185], v[206:209], v[88:91]
	v_mfma_f32_16x16x32_bf16 v[80:83], v[174:177], v[214:217], v[80:83]
	v_mfma_f32_16x16x32_bf16 v[72:75], v[182:185], v[214:217], v[72:75]
	v_mfma_f32_16x16x32_bf16 v[68:71], v[174:177], v[222:225], v[68:71]
	v_mfma_f32_16x16x32_bf16 v[64:67], v[182:185], v[222:225], v[64:67]
	s_setprio 0
	s_barrier
	s_add_i32 s0, s73, s75
	v_lshl_add_u64 v[166:167], v[166:167], 0, s[8:9]
	s_mov_b32 m0, s0
	ds_read_b128 v[194:197], v153 offset:49152
	ds_read_b128 v[198:201], v153 offset:50176
	ds_read_b128 v[202:205], v153 offset:51200
	ds_read_b128 v[206:209], v153 offset:52224
	ds_read_b128 v[210:213], v153 offset:53248
	ds_read_b128 v[214:217], v153 offset:54272
	ds_read_b128 v[218:221], v153 offset:55296
	ds_read_b128 v[222:225], v153 offset:56320
	global_load_lds_dwordx4 v[166:167], off
	s_add_i32 m0, s0, 0x2000
	s_add_u32 s0, s88, 0x40080
	v_lshl_add_u64 v[166:167], v[168:169], 0, s[8:9]
	s_addc_u32 s1, s89, 0
	s_add_i32 s16, s16, s75
	global_load_lds_dwordx4 v[166:167], off
	v_lshl_add_u64 v[166:167], s[0:1], 0, v[130:131]
	s_mov_b32 m0, s16
	s_nop 0
	global_load_lds_dwordx4 v[166:167], off
	v_lshl_add_u64 v[166:167], s[0:1], 0, v[134:135]
	s_add_i32 m0, s16, 0x2000
	s_nop 0
	global_load_lds_dwordx4 v[166:167], off
	v_lshl_add_u64 v[166:167], v[186:187], 0, s[8:9]
	s_mov_b32 m0, s15
	s_nop 0
	global_load_lds_dwordx4 v[166:167], off
	v_lshl_add_u64 v[166:167], v[190:191], 0, s[8:9]
	s_mov_b32 m0, s94
	s_nop 0
	global_load_lds_dwordx4 v[166:167], off
	s_waitcnt vmcnt(8)
	s_waitcnt lgkmcnt(0)
	s_barrier
	s_setprio 1
	s_waitcnt lgkmcnt(0)
	v_mfma_f32_16x16x32_bf16 v[60:63], v[144:147], v[194:197], v[60:63]
	v_mfma_f32_16x16x32_bf16 v[56:59], v[158:161], v[194:197], v[56:59]
	v_mfma_f32_16x16x32_bf16 v[52:55], v[144:147], v[202:205], v[52:55]
	v_mfma_f32_16x16x32_bf16 v[44:47], v[158:161], v[202:205], v[44:47]
	v_mfma_f32_16x16x32_bf16 v[36:39], v[144:147], v[210:213], v[36:39]
	v_mfma_f32_16x16x32_bf16 v[28:31], v[158:161], v[210:213], v[28:31]
	v_mfma_f32_16x16x32_bf16 v[20:23], v[144:147], v[218:221], v[20:23]
	v_mfma_f32_16x16x32_bf16 v[12:15], v[158:161], v[218:221], v[12:15]
	v_mfma_f32_16x16x32_bf16 v[60:63], v[154:157], v[198:201], v[60:63]
	v_mfma_f32_16x16x32_bf16 v[56:59], v[162:165], v[198:201], v[56:59]
	v_mfma_f32_16x16x32_bf16 v[52:55], v[154:157], v[206:209], v[52:55]
	v_mfma_f32_16x16x32_bf16 v[44:47], v[162:165], v[206:209], v[44:47]
	v_mfma_f32_16x16x32_bf16 v[36:39], v[154:157], v[214:217], v[36:39]
	v_mfma_f32_16x16x32_bf16 v[28:31], v[162:165], v[214:217], v[28:31]
	v_mfma_f32_16x16x32_bf16 v[20:23], v[154:157], v[222:225], v[20:23]
	v_mfma_f32_16x16x32_bf16 v[12:15], v[162:165], v[222:225], v[12:15]
	s_setprio 0
	s_setprio 1
	v_mfma_f32_16x16x32_bf16 v[48:51], v[170:173], v[194:197], v[48:51]
	v_mfma_f32_16x16x32_bf16 v[40:43], v[178:181], v[194:197], v[40:43]
	v_mfma_f32_16x16x32_bf16 v[32:35], v[170:173], v[202:205], v[32:35]
	v_mfma_f32_16x16x32_bf16 v[24:27], v[178:181], v[202:205], v[24:27]
	v_mfma_f32_16x16x32_bf16 v[16:19], v[170:173], v[210:213], v[16:19]
	v_mfma_f32_16x16x32_bf16 v[8:11], v[178:181], v[210:213], v[8:11]
	v_mfma_f32_16x16x32_bf16 v[4:7], v[170:173], v[218:221], v[4:7]
	v_mfma_f32_16x16x32_bf16 v[0:3], v[178:181], v[218:221], v[0:3]
	v_mfma_f32_16x16x32_bf16 v[48:51], v[174:177], v[198:201], v[48:51]
	v_mfma_f32_16x16x32_bf16 v[40:43], v[182:185], v[198:201], v[40:43]
	v_mfma_f32_16x16x32_bf16 v[32:35], v[174:177], v[206:209], v[32:35]
	v_mfma_f32_16x16x32_bf16 v[24:27], v[182:185], v[206:209], v[24:27]
	v_mfma_f32_16x16x32_bf16 v[16:19], v[174:177], v[214:217], v[16:19]
	v_mfma_f32_16x16x32_bf16 v[8:11], v[182:185], v[214:217], v[8:11]
	v_mfma_f32_16x16x32_bf16 v[4:7], v[174:177], v[222:225], v[4:7]
	v_mfma_f32_16x16x32_bf16 v[0:3], v[182:185], v[222:225], v[0:3]
	s_setprio 0
	s_barrier
	s_add_i32 s72, s72, 2
	s_add_u32 s86, s86, 0x100
	s_addc_u32 s87, s87, 0
	s_add_u32 s70, s70, 0x100
	s_addc_u32 s71, s71, 0
	s_cmp_gt_u32 s72, 13
	s_cbranch_scc0 .LBB0_162
	s_and_b64 vcc, exec, s[10:11]
	s_cbranch_vccz .LBB0_165
	s_barrier

.LBB0_599:
	s_ashr_i32 s25, s24, 31
	s_lshl_b64 s[18:19], s[24:25], 19
	s_add_u32 s38, s34, s18
	s_addc_u32 s39, s35, s19
	s_and_b64 s[18:19], s[2:3], exec
	s_cselect_b32 s18, s39, s47
	s_cselect_b32 s19, s38, s46
	s_ashr_i32 s23, s22, 31
	s_lshl_b64 s[40:41], s[22:23], 19
	s_add_u32 s40, s74, s40
	s_addc_u32 s41, s75, s41
	s_and_b64 s[50:51], s[2:3], exec
	s_cselect_b32 s23, s41, s49
	s_cselect_b32 s25, s40, s48
	v_lshl_add_u32 v0, s24, 8, v148
	s_add_u32 s46, s46, 0x40080
	s_waitcnt lgkmcnt(0)
	v_ashrrev_i32_e32 v1, 31, v0
	s_addc_u32 s47, s47, 0
	v_lshl_add_u64 v[144:145], v[0:1], 2, s[6:7]
	s_add_u32 s33, s48, 0x100
	s_addc_u32 s43, s49, 0
	s_mov_b32 s63, -2
	s_waitcnt vmcnt(2)
	v_mov_b32_e32 v163, v154
	v_mov_b32_e32 v162, v155
	v_mov_b32_e32 v161, v164
	v_mov_b32_e32 v160, v165
	v_mov_b32_e32 v159, v166
	v_mov_b32_e32 v158, v167
	v_mov_b32_e32 v157, v168
	v_mov_b32_e32 v156, v169
	s_mov_b64 s[48:49], 0
	v_add_u32_e32 v146, s61, v149
	ds_read_b128 v[170:173], v146
	ds_read_b128 v[174:177], v146 offset:1024
	ds_read_b128 v[178:181], v146 offset:2048
	ds_read_b128 v[182:185], v146 offset:3072
	v_add_u32_e32 v146, s62, v149
	ds_read_b128 v[190:193], v146
	ds_read_b128 v[194:197], v146 offset:1024
	ds_read_b128 v[198:201], v146 offset:2048
	ds_read_b128 v[202:205], v146 offset:3072
	s_add_u32 s16, s46, 0xfffc0080
	s_addc_u32 s50, s47, -1
	s_and_b64 s[48:49], s[48:49], exec
	s_cselect_b32 s51, s18, s50
	s_cselect_b32 s50, s19, s16
	s_cselect_b32 s49, s23, s43
	s_cselect_b32 s48, s25, s33
	v_lshl_add_u64 v[146:147], s[46:47], 0, v[136:137]
	s_add_i32 m0, s45, 0xc000
	ds_read_b128 v[206:209], v151
	ds_read_b128 v[210:213], v151 offset:1024
	ds_read_b128 v[214:217], v151 offset:2048
	ds_read_b128 v[218:221], v151 offset:3072
	ds_read_b128 v[222:225], v151 offset:4096
	ds_read_b128 v[226:229], v151 offset:5120
	ds_read_b128 v[230:233], v151 offset:6144
	ds_read_b128 v[234:237], v151 offset:7168
	global_load_lds_dwordx4 v[146:147], off
	v_lshl_add_u64 v[146:147], s[46:47], 0, v[138:139]
	s_add_i32 m0, s45, 0xe000
	s_nop 0
	global_load_lds_dwordx4 v[146:147], off
	s_waitcnt vmcnt(8)
	s_waitcnt lgkmcnt(0)
	s_barrier
	s_setprio 1
	s_waitcnt lgkmcnt(0)
	v_mfma_f32_16x16x32_bf16 v[124:127], v[170:173], v[206:209], 0
	v_mfma_f32_16x16x32_bf16 v[120:123], v[178:181], v[206:209], 0
	v_mfma_f32_16x16x32_bf16 v[108:111], v[170:173], v[214:217], 0
	v_mfma_f32_16x16x32_bf16 v[104:107], v[178:181], v[214:217], 0
	v_mfma_f32_16x16x32_bf16 v[92:95], v[170:173], v[222:225], 0
	v_mfma_f32_16x16x32_bf16 v[88:91], v[178:181], v[222:225], 0
	v_mfma_f32_16x16x32_bf16 v[76:79], v[170:173], v[230:233], 0
	v_mfma_f32_16x16x32_bf16 v[72:75], v[178:181], v[230:233], 0
	v_mfma_f32_16x16x32_bf16 v[124:127], v[174:177], v[210:213], v[124:127]
	v_mfma_f32_16x16x32_bf16 v[120:123], v[182:185], v[210:213], v[120:123]
	v_mfma_f32_16x16x32_bf16 v[108:111], v[174:177], v[218:221], v[108:111]
	v_mfma_f32_16x16x32_bf16 v[104:107], v[182:185], v[218:221], v[104:107]
	v_mfma_f32_16x16x32_bf16 v[92:95], v[174:177], v[226:229], v[92:95]
	v_mfma_f32_16x16x32_bf16 v[88:91], v[182:185], v[226:229], v[88:91]
	v_mfma_f32_16x16x32_bf16 v[76:79], v[174:177], v[234:237], v[76:79]
	v_mfma_f32_16x16x32_bf16 v[72:75], v[182:185], v[234:237], v[72:75]
	s_setprio 0
	s_setprio 1
	v_mfma_f32_16x16x32_bf16 v[116:119], v[190:193], v[206:209], 0
	v_mfma_f32_16x16x32_bf16 v[112:115], v[198:201], v[206:209], 0
	v_mfma_f32_16x16x32_bf16 v[100:103], v[190:193], v[214:217], 0
	v_mfma_f32_16x16x32_bf16 v[96:99], v[198:201], v[214:217], 0
	v_mfma_f32_16x16x32_bf16 v[84:87], v[190:193], v[222:225], 0
	v_mfma_f32_16x16x32_bf16 v[80:83], v[198:201], v[222:225], 0
	v_mfma_f32_16x16x32_bf16 v[68:71], v[190:193], v[230:233], 0
	v_mfma_f32_16x16x32_bf16 v[64:67], v[198:201], v[230:233], 0
	v_mfma_f32_16x16x32_bf16 v[116:119], v[194:197], v[210:213], v[116:119]
	v_mfma_f32_16x16x32_bf16 v[112:115], v[202:205], v[210:213], v[112:115]
	v_mfma_f32_16x16x32_bf16 v[100:103], v[194:197], v[218:221], v[100:103]
	v_mfma_f32_16x16x32_bf16 v[96:99], v[202:205], v[218:221], v[96:99]
	v_mfma_f32_16x16x32_bf16 v[84:87], v[194:197], v[226:229], v[84:87]
	v_mfma_f32_16x16x32_bf16 v[80:83], v[202:205], v[226:229], v[80:83]
	v_mfma_f32_16x16x32_bf16 v[68:71], v[194:197], v[234:237], v[68:71]
	v_mfma_f32_16x16x32_bf16 v[64:67], v[202:205], v[234:237], v[64:67]
	s_setprio 0
	s_barrier
	s_add_i32 s16, s61, s52
	v_lshl_add_u64 v[146:147], s[48:49], 0, v[130:131]
	s_mov_b32 m0, s16
	ds_read_b128 v[206:209], v151 offset:16384
	ds_read_b128 v[210:213], v151 offset:17408
	ds_read_b128 v[214:217], v151 offset:18432
	ds_read_b128 v[218:221], v151 offset:19456
	ds_read_b128 v[222:225], v151 offset:20480
	ds_read_b128 v[226:229], v151 offset:21504
	ds_read_b128 v[230:233], v151 offset:22528
	ds_read_b128 v[234:237], v151 offset:23552
	global_load_lds_dwordx4 v[146:147], off
	s_add_i32 m0, s16, 0x2000
	s_add_u32 s64, s48, 0x40000
	v_lshl_add_u64 v[186:187], s[48:49], 0, v[134:135]
	s_addc_u32 s65, s49, 0
	s_add_i32 s16, s62, s52
	global_load_lds_dwordx4 v[186:187], off
	v_lshl_add_u64 v[238:239], s[64:65], 0, v[130:131]
	s_mov_b32 m0, s16
	v_lshl_add_u64 v[240:241], s[50:51], 0, v[132:133]
	global_load_lds_dwordx4 v[238:239], off
	v_lshl_add_u64 v[238:239], s[64:65], 0, v[134:135]
	s_add_i32 m0, s16, 0x2000
	s_nop 0
	global_load_lds_dwordx4 v[238:239], off
	v_lshl_add_u64 v[238:239], s[50:51], 0, v[128:129]
	s_mov_b32 m0, s45
	s_nop 0
	global_load_lds_dwordx4 v[238:239], off
	s_mov_b32 m0, s53
	s_nop 0
	global_load_lds_dwordx4 v[240:241], off
	s_waitcnt vmcnt(8)
	s_waitcnt lgkmcnt(0)
	s_barrier
	s_setprio 1
	s_waitcnt lgkmcnt(0)
	v_mfma_f32_16x16x32_bf16 v[60:63], v[170:173], v[206:209], 0
	v_mfma_f32_16x16x32_bf16 v[56:59], v[178:181], v[206:209], 0
	v_mfma_f32_16x16x32_bf16 v[44:47], v[170:173], v[214:217], 0
	v_mfma_f32_16x16x32_bf16 v[40:43], v[178:181], v[214:217], 0
	v_mfma_f32_16x16x32_bf16 v[28:31], v[170:173], v[222:225], 0
	v_mfma_f32_16x16x32_bf16 v[24:27], v[178:181], v[222:225], 0
	v_mfma_f32_16x16x32_bf16 v[12:15], v[170:173], v[230:233], 0
	v_mfma_f32_16x16x32_bf16 v[8:11], v[178:181], v[230:233], 0
	v_mfma_f32_16x16x32_bf16 v[60:63], v[174:177], v[210:213], v[60:63]
	v_mfma_f32_16x16x32_bf16 v[56:59], v[182:185], v[210:213], v[56:59]
	v_mfma_f32_16x16x32_bf16 v[44:47], v[174:177], v[218:221], v[44:47]
	v_mfma_f32_16x16x32_bf16 v[40:43], v[182:185], v[218:221], v[40:43]
	v_mfma_f32_16x16x32_bf16 v[28:31], v[174:177], v[226:229], v[28:31]
	v_mfma_f32_16x16x32_bf16 v[24:27], v[182:185], v[226:229], v[24:27]
	v_mfma_f32_16x16x32_bf16 v[12:15], v[174:177], v[234:237], v[12:15]
	v_mfma_f32_16x16x32_bf16 v[8:11], v[182:185], v[234:237], v[8:11]
	s_setprio 0
	s_setprio 1
	v_mfma_f32_16x16x32_bf16 v[52:55], v[190:193], v[206:209], 0
	v_mfma_f32_16x16x32_bf16 v[48:51], v[198:201], v[206:209], 0
	v_mfma_f32_16x16x32_bf16 v[36:39], v[190:193], v[214:217], 0
	v_mfma_f32_16x16x32_bf16 v[32:35], v[198:201], v[214:217], 0
	v_mfma_f32_16x16x32_bf16 v[20:23], v[190:193], v[222:225], 0
	v_mfma_f32_16x16x32_bf16 v[16:19], v[198:201], v[222:225], 0
	v_mfma_f32_16x16x32_bf16 v[4:7], v[190:193], v[230:233], 0
	v_mfma_f32_16x16x32_bf16 v[0:3], v[198:201], v[230:233], 0
	v_mfma_f32_16x16x32_bf16 v[52:55], v[194:197], v[210:213], v[52:55]
	v_mfma_f32_16x16x32_bf16 v[48:51], v[202:205], v[210:213], v[48:51]
	v_mfma_f32_16x16x32_bf16 v[36:39], v[194:197], v[218:221], v[36:39]
	v_mfma_f32_16x16x32_bf16 v[32:35], v[202:205], v[218:221], v[32:35]
	v_mfma_f32_16x16x32_bf16 v[20:23], v[194:197], v[226:229], v[20:23]
	v_mfma_f32_16x16x32_bf16 v[16:19], v[202:205], v[226:229], v[16:19]
	v_mfma_f32_16x16x32_bf16 v[4:7], v[194:197], v[234:237], v[4:7]
	v_mfma_f32_16x16x32_bf16 v[0:3], v[202:205], v[234:237], v[0:3]
	s_setprio 0
	s_barrier
	s_branch .Lpeelp5_mid

.Lpeelp5_mid:
	s_add_i32 s16, 0, 0x18000
	s_add_i32 s64, 0, 0x1c000
	v_add_u32_e32 v182, s16, v149
	v_add_u32_e32 v188, s64, v149
	ds_read_b128 v[170:173], v182
	ds_read_b128 v[174:177], v182 offset:1024
	ds_read_b128 v[178:181], v182 offset:2048
	ds_read_b128 v[182:185], v182 offset:3072
	ds_read_b128 v[190:193], v188
	ds_read_b128 v[194:197], v188 offset:1024
	ds_read_b128 v[198:201], v188 offset:2048
	ds_read_b128 v[202:205], v188 offset:3072
	s_add_u32 s50, s50, 0x40000
	s_addc_u32 s51, s51, 0
	s_mov_b32 m0, s54
	v_lshl_add_u64 v[242:243], s[50:51], 0, v[128:129]
	ds_read_b128 v[206:209], v151 offset:32768
	ds_read_b128 v[210:213], v151 offset:33792
	ds_read_b128 v[214:217], v151 offset:34816
	ds_read_b128 v[218:221], v151 offset:35840
	ds_read_b128 v[222:225], v151 offset:36864
	ds_read_b128 v[226:229], v151 offset:37888
	ds_read_b128 v[230:233], v151 offset:38912
	ds_read_b128 v[234:237], v151 offset:39936
	global_load_lds_dwordx4 v[242:243], off
	v_lshl_add_u64 v[242:243], s[50:51], 0, v[132:133]
	s_mov_b32 m0, s55
	s_nop 0
	global_load_lds_dwordx4 v[242:243], off
	s_waitcnt vmcnt(8)
	s_waitcnt lgkmcnt(0)
	s_barrier
	s_setprio 1
	s_waitcnt lgkmcnt(0)
	v_mfma_f32_16x16x32_bf16 v[124:127], v[170:173], v[206:209], v[124:127]
	v_mfma_f32_16x16x32_bf16 v[120:123], v[178:181], v[206:209], v[120:123]
	v_mfma_f32_16x16x32_bf16 v[108:111], v[170:173], v[214:217], v[108:111]
	v_mfma_f32_16x16x32_bf16 v[104:107], v[178:181], v[214:217], v[104:107]
	v_mfma_f32_16x16x32_bf16 v[92:95], v[170:173], v[222:225], v[92:95]
	v_mfma_f32_16x16x32_bf16 v[88:91], v[178:181], v[222:225], v[88:91]
	v_mfma_f32_16x16x32_bf16 v[76:79], v[170:173], v[230:233], v[76:79]
	v_mfma_f32_16x16x32_bf16 v[72:75], v[178:181], v[230:233], v[72:75]
	v_mfma_f32_16x16x32_bf16 v[124:127], v[174:177], v[210:213], v[124:127]
	v_mfma_f32_16x16x32_bf16 v[120:123], v[182:185], v[210:213], v[120:123]
	v_mfma_f32_16x16x32_bf16 v[108:111], v[174:177], v[218:221], v[108:111]
	v_mfma_f32_16x16x32_bf16 v[104:107], v[182:185], v[218:221], v[104:107]
	v_mfma_f32_16x16x32_bf16 v[92:95], v[174:177], v[226:229], v[92:95]
	v_mfma_f32_16x16x32_bf16 v[88:91], v[182:185], v[226:229], v[88:91]
	v_mfma_f32_16x16x32_bf16 v[76:79], v[174:177], v[234:237], v[76:79]
	v_mfma_f32_16x16x32_bf16 v[72:75], v[182:185], v[234:237], v[72:75]
	s_setprio 0
	s_setprio 1
	v_mfma_f32_16x16x32_bf16 v[116:119], v[190:193], v[206:209], v[116:119]
	v_mfma_f32_16x16x32_bf16 v[112:115], v[198:201], v[206:209], v[112:115]
	v_mfma_f32_16x16x32_bf16 v[100:103], v[190:193], v[214:217], v[100:103]
	v_mfma_f32_16x16x32_bf16 v[96:99], v[198:201], v[214:217], v[96:99]
	v_mfma_f32_16x16x32_bf16 v[84:87], v[190:193], v[222:225], v[84:87]
	v_mfma_f32_16x16x32_bf16 v[80:83], v[198:201], v[222:225], v[80:83]
	v_mfma_f32_16x16x32_bf16 v[68:71], v[190:193], v[230:233], v[68:71]
	v_mfma_f32_16x16x32_bf16 v[64:67], v[198:201], v[230:233], v[64:67]
	v_mfma_f32_16x16x32_bf16 v[116:119], v[194:197], v[210:213], v[116:119]
	v_mfma_f32_16x16x32_bf16 v[112:115], v[202:205], v[210:213], v[112:115]
	v_mfma_f32_16x16x32_bf16 v[100:103], v[194:197], v[218:221], v[100:103]
	v_mfma_f32_16x16x32_bf16 v[96:99], v[202:205], v[218:221], v[96:99]
	v_mfma_f32_16x16x32_bf16 v[84:87], v[194:197], v[226:229], v[84:87]
	v_mfma_f32_16x16x32_bf16 v[80:83], v[202:205], v[226:229], v[80:83]
	v_mfma_f32_16x16x32_bf16 v[68:71], v[194:197], v[234:237], v[68:71]
	v_mfma_f32_16x16x32_bf16 v[64:67], v[202:205], v[234:237], v[64:67]
	s_setprio 0
	s_barrier
	s_add_i32 s16, s16, s52
	v_lshl_add_u64 v[146:147], v[146:147], 0, s[14:15]
	s_mov_b32 m0, s16
	ds_read_b128 v[206:209], v151 offset:49152
	ds_read_b128 v[210:213], v151 offset:50176
	ds_read_b128 v[214:217], v151 offset:51200
	ds_read_b128 v[218:221], v151 offset:52224
	ds_read_b128 v[222:225], v151 offset:53248
	ds_read_b128 v[226:229], v151 offset:54272
	ds_read_b128 v[230:233], v151 offset:55296
	ds_read_b128 v[234:237], v151 offset:56320
	global_load_lds_dwordx4 v[146:147], off
	s_add_i32 m0, s16, 0x2000
	s_add_u32 s48, s48, 0x40080
	v_lshl_add_u64 v[146:147], v[186:187], 0, s[14:15]
	s_addc_u32 s49, s49, 0
	s_add_i32 s16, s64, s52
	global_load_lds_dwordx4 v[146:147], off
	v_lshl_add_u64 v[146:147], s[48:49], 0, v[130:131]
	s_mov_b32 m0, s16
	s_nop 0
	global_load_lds_dwordx4 v[146:147], off
	v_lshl_add_u64 v[146:147], s[48:49], 0, v[134:135]
	s_add_i32 m0, s16, 0x2000
	s_nop 0
	global_load_lds_dwordx4 v[146:147], off
	v_lshl_add_u64 v[146:147], v[238:239], 0, s[14:15]
	s_mov_b32 m0, s59
	s_nop 0
	global_load_lds_dwordx4 v[146:147], off
	v_lshl_add_u64 v[146:147], v[240:241], 0, s[14:15]
	s_mov_b32 m0, s60
	s_nop 0
	global_load_lds_dwordx4 v[146:147], off
	s_waitcnt vmcnt(8)
	s_waitcnt lgkmcnt(0)
	s_barrier
	s_setprio 1
	s_waitcnt lgkmcnt(0)
	v_mfma_f32_16x16x32_bf16 v[60:63], v[170:173], v[206:209], v[60:63]
	v_mfma_f32_16x16x32_bf16 v[56:59], v[178:181], v[206:209], v[56:59]
	v_mfma_f32_16x16x32_bf16 v[44:47], v[170:173], v[214:217], v[44:47]
	v_mfma_f32_16x16x32_bf16 v[40:43], v[178:181], v[214:217], v[40:43]
	v_mfma_f32_16x16x32_bf16 v[28:31], v[170:173], v[222:225], v[28:31]
	v_mfma_f32_16x16x32_bf16 v[24:27], v[178:181], v[222:225], v[24:27]
	v_mfma_f32_16x16x32_bf16 v[12:15], v[170:173], v[230:233], v[12:15]
	v_mfma_f32_16x16x32_bf16 v[8:11], v[178:181], v[230:233], v[8:11]
	v_mfma_f32_16x16x32_bf16 v[60:63], v[174:177], v[210:213], v[60:63]
	v_mfma_f32_16x16x32_bf16 v[56:59], v[182:185], v[210:213], v[56:59]
	v_mfma_f32_16x16x32_bf16 v[44:47], v[174:177], v[218:221], v[44:47]
	v_mfma_f32_16x16x32_bf16 v[40:43], v[182:185], v[218:221], v[40:43]
	v_mfma_f32_16x16x32_bf16 v[28:31], v[174:177], v[226:229], v[28:31]
	v_mfma_f32_16x16x32_bf16 v[24:27], v[182:185], v[226:229], v[24:27]
	v_mfma_f32_16x16x32_bf16 v[12:15], v[174:177], v[234:237], v[12:15]
	v_mfma_f32_16x16x32_bf16 v[8:11], v[182:185], v[234:237], v[8:11]
	s_setprio 0
	s_setprio 1
	v_mfma_f32_16x16x32_bf16 v[52:55], v[190:193], v[206:209], v[52:55]
	v_mfma_f32_16x16x32_bf16 v[48:51], v[198:201], v[206:209], v[48:51]
	v_mfma_f32_16x16x32_bf16 v[36:39], v[190:193], v[214:217], v[36:39]
	v_mfma_f32_16x16x32_bf16 v[32:35], v[198:201], v[214:217], v[32:35]
	v_mfma_f32_16x16x32_bf16 v[20:23], v[190:193], v[222:225], v[20:23]
	v_mfma_f32_16x16x32_bf16 v[16:19], v[198:201], v[222:225], v[16:19]
	v_mfma_f32_16x16x32_bf16 v[4:7], v[190:193], v[230:233], v[4:7]
	v_mfma_f32_16x16x32_bf16 v[0:3], v[198:201], v[230:233], v[0:3]
	v_mfma_f32_16x16x32_bf16 v[52:55], v[194:197], v[210:213], v[52:55]
	v_mfma_f32_16x16x32_bf16 v[48:51], v[202:205], v[210:213], v[48:51]
	v_mfma_f32_16x16x32_bf16 v[36:39], v[194:197], v[218:221], v[36:39]
	v_mfma_f32_16x16x32_bf16 v[32:35], v[202:205], v[218:221], v[32:35]
	v_mfma_f32_16x16x32_bf16 v[20:23], v[194:197], v[226:229], v[20:23]
	v_mfma_f32_16x16x32_bf16 v[16:19], v[202:205], v[226:229], v[16:19]
	v_mfma_f32_16x16x32_bf16 v[4:7], v[194:197], v[234:237], v[4:7]
	v_mfma_f32_16x16x32_bf16 v[0:3], v[202:205], v[234:237], v[0:3]
	s_setprio 0
	s_barrier
	s_add_i32 s63, s63, 2
	s_add_u32 s46, s46, 0x100
	s_addc_u32 s47, s47, 0
	s_add_u32 s33, s33, 0x100
	s_addc_u32 s43, s43, 0
	s_cmp_gt_u32 s63, 13
	s_cbranch_scc1 .LBB0_603

.LBB0_684:
	s_ashr_i32 s21, s20, 31
	s_lshl_b64 s[22:23], s[20:21], 19
	s_add_u32 s22, s4, s22
	s_addc_u32 s23, s5, s23
	s_and_b64 s[24:25], s[0:1], exec
	s_cselect_b32 s19, s23, s41
	s_cselect_b32 s21, s22, s40
	s_ashr_i32 s15, s14, 31
	s_lshl_b64 s[24:25], s[14:15], 19
	s_add_u32 s24, s72, s24
	s_addc_u32 s25, s73, s25
	s_and_b64 s[42:43], s[0:1], exec
	s_cselect_b32 s15, s25, s39
	s_cselect_b32 s33, s24, s38
	v_lshl_add_u32 v0, s20, 8, v146
	s_add_u32 s57, s38, 0x100
	v_ashrrev_i32_e32 v1, 31, v0
	s_addc_u32 s58, s39, 0
	v_lshl_add_u64 v[144:145], v[0:1], 2, s[8:9]
	s_add_u32 s38, s40, 0x40080
	s_addc_u32 s39, s41, 0
	s_mov_b32 s59, -2
	s_waitcnt vmcnt(8)
	v_mov_b32_e32 v153, v166
	v_mov_b32_e32 v154, v165
	v_mov_b32_e32 v155, v164
	v_mov_b32_e32 v156, v163
	v_mov_b32_e32 v157, v162
	v_mov_b32_e32 v158, v161
	v_mov_b32_e32 v159, v152
	v_mov_b32_e32 v160, v149
	s_mov_b64 s[40:41], 0
	v_add_u32_e32 v167, s54, v147
	ds_read_b128 v[168:171], v167
	ds_read_b128 v[172:175], v167 offset:1024
	ds_read_b128 v[176:179], v167 offset:2048
	ds_read_b128 v[180:183], v167 offset:3072
	v_add_u32_e32 v167, s55, v147
	ds_read_b128 v[184:187], v167
	ds_read_b128 v[190:193], v167 offset:1024
	ds_read_b128 v[194:197], v167 offset:2048
	ds_read_b128 v[198:201], v167 offset:3072
	s_add_u32 s16, s38, 0xfffc0080
	s_addc_u32 s42, s39, -1
	s_and_b64 s[40:41], s[40:41], exec
	s_cselect_b32 s43, s19, s42
	s_cselect_b32 s42, s21, s16
	s_cselect_b32 s41, s15, s58
	s_cselect_b32 s40, s33, s57
	v_lshl_add_u64 v[234:235], s[38:39], 0, v[136:137]
	s_add_i32 m0, s37, 0xc000
	ds_read_b128 v[202:205], v150
	ds_read_b128 v[206:209], v150 offset:1024
	ds_read_b128 v[210:213], v150 offset:2048
	ds_read_b128 v[214:217], v150 offset:3072
	ds_read_b128 v[218:221], v150 offset:4096
	ds_read_b128 v[222:225], v150 offset:5120
	ds_read_b128 v[226:229], v150 offset:6144
	ds_read_b128 v[230:233], v150 offset:7168
	global_load_lds_dwordx4 v[234:235], off
	v_lshl_add_u64 v[234:235], s[38:39], 0, v[138:139]
	s_add_i32 m0, s37, 0xe000
	s_nop 0
	global_load_lds_dwordx4 v[234:235], off
	s_waitcnt vmcnt(8)
	s_waitcnt lgkmcnt(0)
	s_barrier
	s_setprio 1
	s_waitcnt lgkmcnt(0)
	v_mfma_f32_16x16x32_bf16 v[124:127], v[168:171], v[202:205], 0
	v_mfma_f32_16x16x32_bf16 v[116:119], v[176:179], v[202:205], 0
	v_mfma_f32_16x16x32_bf16 v[108:111], v[168:171], v[210:213], 0
	v_mfma_f32_16x16x32_bf16 v[100:103], v[176:179], v[210:213], 0
	v_mfma_f32_16x16x32_bf16 v[92:95], v[168:171], v[218:221], 0
	v_mfma_f32_16x16x32_bf16 v[84:87], v[176:179], v[218:221], 0
	v_mfma_f32_16x16x32_bf16 v[76:79], v[168:171], v[226:229], 0
	v_mfma_f32_16x16x32_bf16 v[68:71], v[176:179], v[226:229], 0
	v_mfma_f32_16x16x32_bf16 v[124:127], v[172:175], v[206:209], v[124:127]
	v_mfma_f32_16x16x32_bf16 v[116:119], v[180:183], v[206:209], v[116:119]
	v_mfma_f32_16x16x32_bf16 v[108:111], v[172:175], v[214:217], v[108:111]
	v_mfma_f32_16x16x32_bf16 v[100:103], v[180:183], v[214:217], v[100:103]
	v_mfma_f32_16x16x32_bf16 v[92:95], v[172:175], v[222:225], v[92:95]
	v_mfma_f32_16x16x32_bf16 v[84:87], v[180:183], v[222:225], v[84:87]
	v_mfma_f32_16x16x32_bf16 v[76:79], v[172:175], v[230:233], v[76:79]
	v_mfma_f32_16x16x32_bf16 v[68:71], v[180:183], v[230:233], v[68:71]
	s_setprio 0
	s_setprio 1
	v_mfma_f32_16x16x32_bf16 v[120:123], v[184:187], v[202:205], 0
	v_mfma_f32_16x16x32_bf16 v[112:115], v[194:197], v[202:205], 0
	v_mfma_f32_16x16x32_bf16 v[104:107], v[184:187], v[210:213], 0
	v_mfma_f32_16x16x32_bf16 v[96:99], v[194:197], v[210:213], 0
	v_mfma_f32_16x16x32_bf16 v[88:91], v[184:187], v[218:221], 0
	v_mfma_f32_16x16x32_bf16 v[80:83], v[194:197], v[218:221], 0
	v_mfma_f32_16x16x32_bf16 v[72:75], v[184:187], v[226:229], 0
	v_mfma_f32_16x16x32_bf16 v[64:67], v[194:197], v[226:229], 0
	v_mfma_f32_16x16x32_bf16 v[120:123], v[190:193], v[206:209], v[120:123]
	v_mfma_f32_16x16x32_bf16 v[112:115], v[198:201], v[206:209], v[112:115]
	v_mfma_f32_16x16x32_bf16 v[104:107], v[190:193], v[214:217], v[104:107]
	v_mfma_f32_16x16x32_bf16 v[96:99], v[198:201], v[214:217], v[96:99]
	v_mfma_f32_16x16x32_bf16 v[88:91], v[190:193], v[222:225], v[88:91]
	v_mfma_f32_16x16x32_bf16 v[80:83], v[198:201], v[222:225], v[80:83]
	v_mfma_f32_16x16x32_bf16 v[72:75], v[190:193], v[230:233], v[72:75]
	v_mfma_f32_16x16x32_bf16 v[64:67], v[198:201], v[230:233], v[64:67]
	s_setprio 0
	s_barrier
	s_add_i32 s16, s54, s44
	v_lshl_add_u64 v[234:235], s[40:41], 0, v[130:131]
	s_mov_b32 m0, s16
	ds_read_b128 v[202:205], v150 offset:16384
	ds_read_b128 v[206:209], v150 offset:17408
	ds_read_b128 v[210:213], v150 offset:18432
	ds_read_b128 v[214:217], v150 offset:19456
	ds_read_b128 v[218:221], v150 offset:20480
	ds_read_b128 v[222:225], v150 offset:21504
	ds_read_b128 v[226:229], v150 offset:22528
	ds_read_b128 v[230:233], v150 offset:23552
	global_load_lds_dwordx4 v[234:235], off
	s_add_i32 m0, s16, 0x2000
	s_add_u32 s60, s40, 0x40000
	v_lshl_add_u64 v[236:237], s[40:41], 0, v[134:135]
	s_addc_u32 s61, s41, 0
	s_add_i32 s16, s55, s44
	global_load_lds_dwordx4 v[236:237], off
	v_lshl_add_u64 v[238:239], s[60:61], 0, v[130:131]
	s_mov_b32 m0, s16
	v_lshl_add_u64 v[240:241], s[42:43], 0, v[132:133]
	global_load_lds_dwordx4 v[238:239], off
	v_lshl_add_u64 v[238:239], s[60:61], 0, v[134:135]
	s_add_i32 m0, s16, 0x2000
	s_nop 0
	global_load_lds_dwordx4 v[238:239], off
	v_lshl_add_u64 v[238:239], s[42:43], 0, v[128:129]
	s_mov_b32 m0, s37
	s_nop 0
	global_load_lds_dwordx4 v[238:239], off
	s_mov_b32 m0, s47
	s_nop 0
	global_load_lds_dwordx4 v[240:241], off
	s_waitcnt vmcnt(8)
	s_waitcnt lgkmcnt(0)
	s_barrier
	s_setprio 1
	s_waitcnt lgkmcnt(0)
	v_mfma_f32_16x16x32_bf16 v[60:63], v[168:171], v[202:205], 0
	v_mfma_f32_16x16x32_bf16 v[52:55], v[176:179], v[202:205], 0
	v_mfma_f32_16x16x32_bf16 v[44:47], v[168:171], v[210:213], 0
	v_mfma_f32_16x16x32_bf16 v[36:39], v[176:179], v[210:213], 0
	v_mfma_f32_16x16x32_bf16 v[28:31], v[168:171], v[218:221], 0
	v_mfma_f32_16x16x32_bf16 v[20:23], v[176:179], v[218:221], 0
	v_mfma_f32_16x16x32_bf16 v[12:15], v[168:171], v[226:229], 0
	v_mfma_f32_16x16x32_bf16 v[4:7], v[176:179], v[226:229], 0
	v_mfma_f32_16x16x32_bf16 v[60:63], v[172:175], v[206:209], v[60:63]
	v_mfma_f32_16x16x32_bf16 v[52:55], v[180:183], v[206:209], v[52:55]
	v_mfma_f32_16x16x32_bf16 v[44:47], v[172:175], v[214:217], v[44:47]
	v_mfma_f32_16x16x32_bf16 v[36:39], v[180:183], v[214:217], v[36:39]
	v_mfma_f32_16x16x32_bf16 v[28:31], v[172:175], v[222:225], v[28:31]
	v_mfma_f32_16x16x32_bf16 v[20:23], v[180:183], v[222:225], v[20:23]
	v_mfma_f32_16x16x32_bf16 v[12:15], v[172:175], v[230:233], v[12:15]
	v_mfma_f32_16x16x32_bf16 v[4:7], v[180:183], v[230:233], v[4:7]
	s_setprio 0
	s_setprio 1
	v_mfma_f32_16x16x32_bf16 v[56:59], v[184:187], v[202:205], 0
	v_mfma_f32_16x16x32_bf16 v[48:51], v[194:197], v[202:205], 0
	v_mfma_f32_16x16x32_bf16 v[40:43], v[184:187], v[210:213], 0
	v_mfma_f32_16x16x32_bf16 v[32:35], v[194:197], v[210:213], 0
	v_mfma_f32_16x16x32_bf16 v[24:27], v[184:187], v[218:221], 0
	v_mfma_f32_16x16x32_bf16 v[16:19], v[194:197], v[218:221], 0
	v_mfma_f32_16x16x32_bf16 v[8:11], v[184:187], v[226:229], 0
	v_mfma_f32_16x16x32_bf16 v[0:3], v[194:197], v[226:229], 0
	v_mfma_f32_16x16x32_bf16 v[56:59], v[190:193], v[206:209], v[56:59]
	v_mfma_f32_16x16x32_bf16 v[48:51], v[198:201], v[206:209], v[48:51]
	v_mfma_f32_16x16x32_bf16 v[40:43], v[190:193], v[214:217], v[40:43]
	v_mfma_f32_16x16x32_bf16 v[32:35], v[198:201], v[214:217], v[32:35]
	v_mfma_f32_16x16x32_bf16 v[24:27], v[190:193], v[222:225], v[24:27]
	v_mfma_f32_16x16x32_bf16 v[16:19], v[198:201], v[222:225], v[16:19]
	v_mfma_f32_16x16x32_bf16 v[8:11], v[190:193], v[230:233], v[8:11]
	v_mfma_f32_16x16x32_bf16 v[0:3], v[198:201], v[230:233], v[0:3]
	s_setprio 0
	s_barrier
	s_branch .Lpeelp6_mid

.Lpeelp6_mid:
	s_add_i32 s16, 0, 0x18000
	v_add_u32_e32 v167, s16, v147
	s_add_i32 s60, 0, 0x1c000
	ds_read_b128 v[168:171], v167
	ds_read_b128 v[172:175], v167 offset:1024
	ds_read_b128 v[176:179], v167 offset:2048
	ds_read_b128 v[180:183], v167 offset:3072
	v_add_u32_e32 v167, s60, v147
	ds_read_b128 v[184:187], v167
	ds_read_b128 v[190:193], v167 offset:1024
	ds_read_b128 v[194:197], v167 offset:2048
	ds_read_b128 v[198:201], v167 offset:3072
	s_add_u32 s42, s42, 0x40000
	s_addc_u32 s43, s43, 0
	s_mov_b32 m0, s48
	v_lshl_add_u64 v[242:243], s[42:43], 0, v[128:129]
	ds_read_b128 v[202:205], v150 offset:32768
	ds_read_b128 v[206:209], v150 offset:33792
	ds_read_b128 v[210:213], v150 offset:34816
	ds_read_b128 v[214:217], v150 offset:35840
	ds_read_b128 v[218:221], v150 offset:36864
	ds_read_b128 v[222:225], v150 offset:37888
	ds_read_b128 v[226:229], v150 offset:38912
	ds_read_b128 v[230:233], v150 offset:39936
	global_load_lds_dwordx4 v[242:243], off
	v_lshl_add_u64 v[242:243], s[42:43], 0, v[132:133]
	s_mov_b32 m0, s49
	s_nop 0
	global_load_lds_dwordx4 v[242:243], off
	s_waitcnt vmcnt(8)
	s_waitcnt lgkmcnt(0)
	s_barrier
	s_setprio 1
	s_waitcnt lgkmcnt(0)
	v_mfma_f32_16x16x32_bf16 v[124:127], v[168:171], v[202:205], v[124:127]
	v_mfma_f32_16x16x32_bf16 v[116:119], v[176:179], v[202:205], v[116:119]
	v_mfma_f32_16x16x32_bf16 v[108:111], v[168:171], v[210:213], v[108:111]
	v_mfma_f32_16x16x32_bf16 v[100:103], v[176:179], v[210:213], v[100:103]
	v_mfma_f32_16x16x32_bf16 v[92:95], v[168:171], v[218:221], v[92:95]
	v_mfma_f32_16x16x32_bf16 v[84:87], v[176:179], v[218:221], v[84:87]
	v_mfma_f32_16x16x32_bf16 v[76:79], v[168:171], v[226:229], v[76:79]
	v_mfma_f32_16x16x32_bf16 v[68:71], v[176:179], v[226:229], v[68:71]
	v_mfma_f32_16x16x32_bf16 v[124:127], v[172:175], v[206:209], v[124:127]
	v_mfma_f32_16x16x32_bf16 v[116:119], v[180:183], v[206:209], v[116:119]
	v_mfma_f32_16x16x32_bf16 v[108:111], v[172:175], v[214:217], v[108:111]
	v_mfma_f32_16x16x32_bf16 v[100:103], v[180:183], v[214:217], v[100:103]
	v_mfma_f32_16x16x32_bf16 v[92:95], v[172:175], v[222:225], v[92:95]
	v_mfma_f32_16x16x32_bf16 v[84:87], v[180:183], v[222:225], v[84:87]
	v_mfma_f32_16x16x32_bf16 v[76:79], v[172:175], v[230:233], v[76:79]
	v_mfma_f32_16x16x32_bf16 v[68:71], v[180:183], v[230:233], v[68:71]
	s_setprio 0
	s_setprio 1
	v_mfma_f32_16x16x32_bf16 v[120:123], v[184:187], v[202:205], v[120:123]
	v_mfma_f32_16x16x32_bf16 v[112:115], v[194:197], v[202:205], v[112:115]
	v_mfma_f32_16x16x32_bf16 v[104:107], v[184:187], v[210:213], v[104:107]
	v_mfma_f32_16x16x32_bf16 v[96:99], v[194:197], v[210:213], v[96:99]
	v_mfma_f32_16x16x32_bf16 v[88:91], v[184:187], v[218:221], v[88:91]
	v_mfma_f32_16x16x32_bf16 v[80:83], v[194:197], v[218:221], v[80:83]
	v_mfma_f32_16x16x32_bf16 v[72:75], v[184:187], v[226:229], v[72:75]
	v_mfma_f32_16x16x32_bf16 v[64:67], v[194:197], v[226:229], v[64:67]
	v_mfma_f32_16x16x32_bf16 v[120:123], v[190:193], v[206:209], v[120:123]
	v_mfma_f32_16x16x32_bf16 v[112:115], v[198:201], v[206:209], v[112:115]
	v_mfma_f32_16x16x32_bf16 v[104:107], v[190:193], v[214:217], v[104:107]
	v_mfma_f32_16x16x32_bf16 v[96:99], v[198:201], v[214:217], v[96:99]
	v_mfma_f32_16x16x32_bf16 v[88:91], v[190:193], v[222:225], v[88:91]
	v_mfma_f32_16x16x32_bf16 v[80:83], v[198:201], v[222:225], v[80:83]
	v_mfma_f32_16x16x32_bf16 v[72:75], v[190:193], v[230:233], v[72:75]
	v_mfma_f32_16x16x32_bf16 v[64:67], v[198:201], v[230:233], v[64:67]
	s_setprio 0
	s_barrier
	s_add_i32 s16, s16, s44
	v_lshl_add_u64 v[234:235], v[234:235], 0, s[10:11]
	s_mov_b32 m0, s16
	ds_read_b128 v[202:205], v150 offset:49152
	ds_read_b128 v[206:209], v150 offset:50176
	ds_read_b128 v[210:213], v150 offset:51200
	ds_read_b128 v[214:217], v150 offset:52224
	ds_read_b128 v[218:221], v150 offset:53248
	ds_read_b128 v[222:225], v150 offset:54272
	ds_read_b128 v[226:229], v150 offset:55296
	ds_read_b128 v[230:233], v150 offset:56320
	global_load_lds_dwordx4 v[234:235], off
	s_add_i32 m0, s16, 0x2000
	s_add_u32 s40, s40, 0x40080
	v_lshl_add_u64 v[234:235], v[236:237], 0, s[10:11]
	s_addc_u32 s41, s41, 0
	s_add_i32 s16, s60, s44
	global_load_lds_dwordx4 v[234:235], off
	v_lshl_add_u64 v[234:235], s[40:41], 0, v[130:131]
	s_mov_b32 m0, s16
	s_nop 0
	global_load_lds_dwordx4 v[234:235], off
	v_lshl_add_u64 v[234:235], s[40:41], 0, v[134:135]
	s_add_i32 m0, s16, 0x2000
	s_nop 0
	global_load_lds_dwordx4 v[234:235], off
	v_lshl_add_u64 v[234:235], v[238:239], 0, s[10:11]
	s_mov_b32 m0, s52
	s_nop 0
	global_load_lds_dwordx4 v[234:235], off
	v_lshl_add_u64 v[234:235], v[240:241], 0, s[10:11]
	s_mov_b32 m0, s53
	s_nop 0
	global_load_lds_dwordx4 v[234:235], off
	s_waitcnt vmcnt(8)
	s_waitcnt lgkmcnt(0)
	s_barrier
	s_setprio 1
	s_waitcnt lgkmcnt(0)
	v_mfma_f32_16x16x32_bf16 v[60:63], v[168:171], v[202:205], v[60:63]
	v_mfma_f32_16x16x32_bf16 v[52:55], v[176:179], v[202:205], v[52:55]
	v_mfma_f32_16x16x32_bf16 v[44:47], v[168:171], v[210:213], v[44:47]
	v_mfma_f32_16x16x32_bf16 v[36:39], v[176:179], v[210:213], v[36:39]
	v_mfma_f32_16x16x32_bf16 v[28:31], v[168:171], v[218:221], v[28:31]
	v_mfma_f32_16x16x32_bf16 v[20:23], v[176:179], v[218:221], v[20:23]
	v_mfma_f32_16x16x32_bf16 v[12:15], v[168:171], v[226:229], v[12:15]
	v_mfma_f32_16x16x32_bf16 v[4:7], v[176:179], v[226:229], v[4:7]
	v_mfma_f32_16x16x32_bf16 v[60:63], v[172:175], v[206:209], v[60:63]
	v_mfma_f32_16x16x32_bf16 v[52:55], v[180:183], v[206:209], v[52:55]
	v_mfma_f32_16x16x32_bf16 v[44:47], v[172:175], v[214:217], v[44:47]
	v_mfma_f32_16x16x32_bf16 v[36:39], v[180:183], v[214:217], v[36:39]
	v_mfma_f32_16x16x32_bf16 v[28:31], v[172:175], v[222:225], v[28:31]
	v_mfma_f32_16x16x32_bf16 v[20:23], v[180:183], v[222:225], v[20:23]
	v_mfma_f32_16x16x32_bf16 v[12:15], v[172:175], v[230:233], v[12:15]
	v_mfma_f32_16x16x32_bf16 v[4:7], v[180:183], v[230:233], v[4:7]
	s_setprio 0
	s_setprio 1
	v_mfma_f32_16x16x32_bf16 v[56:59], v[184:187], v[202:205], v[56:59]
	v_mfma_f32_16x16x32_bf16 v[48:51], v[194:197], v[202:205], v[48:51]
	v_mfma_f32_16x16x32_bf16 v[40:43], v[184:187], v[210:213], v[40:43]
	v_mfma_f32_16x16x32_bf16 v[32:35], v[194:197], v[210:213], v[32:35]
	v_mfma_f32_16x16x32_bf16 v[24:27], v[184:187], v[218:221], v[24:27]
	v_mfma_f32_16x16x32_bf16 v[16:19], v[194:197], v[218:221], v[16:19]
	v_mfma_f32_16x16x32_bf16 v[8:11], v[184:187], v[226:229], v[8:11]
	v_mfma_f32_16x16x32_bf16 v[0:3], v[194:197], v[226:229], v[0:3]
	v_mfma_f32_16x16x32_bf16 v[56:59], v[190:193], v[206:209], v[56:59]
	v_mfma_f32_16x16x32_bf16 v[48:51], v[198:201], v[206:209], v[48:51]
	v_mfma_f32_16x16x32_bf16 v[40:43], v[190:193], v[214:217], v[40:43]
	v_mfma_f32_16x16x32_bf16 v[32:35], v[198:201], v[214:217], v[32:35]
	v_mfma_f32_16x16x32_bf16 v[24:27], v[190:193], v[222:225], v[24:27]
	v_mfma_f32_16x16x32_bf16 v[16:19], v[198:201], v[222:225], v[16:19]
	v_mfma_f32_16x16x32_bf16 v[8:11], v[190:193], v[230:233], v[8:11]
	v_mfma_f32_16x16x32_bf16 v[0:3], v[198:201], v[230:233], v[0:3]
	s_setprio 0
	s_barrier
	s_add_i32 s59, s59, 2
	s_add_u32 s57, s57, 0x100
	s_addc_u32 s58, s58, 0
	s_add_u32 s38, s38, 0x100
	s_addc_u32 s39, s39, 0
	s_cmp_gt_u32 s59, 13
	s_cbranch_scc1 .LBB0_688

.LBB0_761:
	s_add_u32 s28, s28, 0xb0080
	s_addc_u32 s29, s29, 0
	s_add_u32 s51, s30, 0x100
	s_addc_u32 s52, s31, 0
	s_mov_b32 s53, -2
	ds_read_b128 v[144:147], v153
	ds_read_b128 v[156:159], v153 offset:1024
	ds_read_b128 v[160:163], v153 offset:2048
	ds_read_b128 v[164:167], v153 offset:3072
	ds_read_b128 v[168:171], v154
	ds_read_b128 v[172:175], v154 offset:1024
	ds_read_b128 v[176:179], v154 offset:2048
	ds_read_b128 v[180:183], v154 offset:3072
	s_add_u32 s16, s28, 0xfff50080
	s_addc_u32 s30, s29, -1
	s_cmp_eq_u32 s53, 40
	s_cselect_b32 s37, s3, s30
	s_cselect_b32 s36, s2, s16
	s_cselect_b32 s31, s25, s52
	s_cselect_b32 s30, s24, s51
	v_lshl_add_u64 v[148:149], s[28:29], 0, v[136:137]
	s_add_i32 m0, s39, 0xc000
	ds_read_b128 v[184:187], v155
	ds_read_b128 v[188:191], v155 offset:1024
	ds_read_b128 v[192:195], v155 offset:2048
	ds_read_b128 v[196:199], v155 offset:3072
	ds_read_b128 v[200:203], v155 offset:4096
	ds_read_b128 v[204:207], v155 offset:5120
	ds_read_b128 v[208:211], v155 offset:6144
	ds_read_b128 v[212:215], v155 offset:7168
	global_load_lds_dwordx4 v[148:149], off
	v_lshl_add_u64 v[148:149], s[28:29], 0, v[138:139]
	s_add_i32 m0, s39, 0xe000
	s_nop 0
	global_load_lds_dwordx4 v[148:149], off
	s_waitcnt vmcnt(8)
	s_waitcnt lgkmcnt(0)
	s_barrier
	s_setprio 1
	s_waitcnt lgkmcnt(0)
	v_mfma_f32_16x16x32_bf16 v[124:127], v[144:147], v[184:187], 0
	v_mfma_f32_16x16x32_bf16 v[120:123], v[160:163], v[184:187], 0
	v_mfma_f32_16x16x32_bf16 v[116:119], v[144:147], v[192:195], 0
	v_mfma_f32_16x16x32_bf16 v[104:107], v[160:163], v[192:195], 0
	v_mfma_f32_16x16x32_bf16 v[100:103], v[144:147], v[200:203], 0
	v_mfma_f32_16x16x32_bf16 v[88:91], v[160:163], v[200:203], 0
	v_mfma_f32_16x16x32_bf16 v[84:87], v[144:147], v[208:211], 0
	v_mfma_f32_16x16x32_bf16 v[72:75], v[160:163], v[208:211], 0
	v_mfma_f32_16x16x32_bf16 v[124:127], v[156:159], v[188:191], v[124:127]
	v_mfma_f32_16x16x32_bf16 v[120:123], v[164:167], v[188:191], v[120:123]
	v_mfma_f32_16x16x32_bf16 v[116:119], v[156:159], v[196:199], v[116:119]
	v_mfma_f32_16x16x32_bf16 v[104:107], v[164:167], v[196:199], v[104:107]
	v_mfma_f32_16x16x32_bf16 v[100:103], v[156:159], v[204:207], v[100:103]
	v_mfma_f32_16x16x32_bf16 v[88:91], v[164:167], v[204:207], v[88:91]
	v_mfma_f32_16x16x32_bf16 v[84:87], v[156:159], v[212:215], v[84:87]
	v_mfma_f32_16x16x32_bf16 v[72:75], v[164:167], v[212:215], v[72:75]
	s_setprio 0
	s_setprio 1
	v_mfma_f32_16x16x32_bf16 v[112:115], v[168:171], v[184:187], 0
	v_mfma_f32_16x16x32_bf16 v[108:111], v[176:179], v[184:187], 0
	v_mfma_f32_16x16x32_bf16 v[96:99], v[168:171], v[192:195], 0
	v_mfma_f32_16x16x32_bf16 v[92:95], v[176:179], v[192:195], 0
	v_mfma_f32_16x16x32_bf16 v[80:83], v[168:171], v[200:203], 0
	v_mfma_f32_16x16x32_bf16 v[76:79], v[176:179], v[200:203], 0
	v_mfma_f32_16x16x32_bf16 v[68:71], v[168:171], v[208:211], 0
	v_mfma_f32_16x16x32_bf16 v[64:67], v[176:179], v[208:211], 0
	v_mfma_f32_16x16x32_bf16 v[112:115], v[172:175], v[188:191], v[112:115]
	v_mfma_f32_16x16x32_bf16 v[108:111], v[180:183], v[188:191], v[108:111]
	v_mfma_f32_16x16x32_bf16 v[96:99], v[172:175], v[196:199], v[96:99]
	v_mfma_f32_16x16x32_bf16 v[92:95], v[180:183], v[196:199], v[92:95]
	v_mfma_f32_16x16x32_bf16 v[80:83], v[172:175], v[204:207], v[80:83]
	v_mfma_f32_16x16x32_bf16 v[76:79], v[180:183], v[204:207], v[76:79]
	v_mfma_f32_16x16x32_bf16 v[68:71], v[172:175], v[212:215], v[68:71]
	v_mfma_f32_16x16x32_bf16 v[64:67], v[180:183], v[212:215], v[64:67]
	s_setprio 0
	s_barrier
	s_add_i32 s16, s47, s33
	v_lshl_add_u64 v[148:149], s[30:31], 0, v[130:131]
	s_mov_b32 m0, s16
	ds_read_b128 v[184:187], v155 offset:16384
	ds_read_b128 v[188:191], v155 offset:17408
	ds_read_b128 v[192:195], v155 offset:18432
	ds_read_b128 v[196:199], v155 offset:19456
	ds_read_b128 v[200:203], v155 offset:20480
	ds_read_b128 v[204:207], v155 offset:21504
	ds_read_b128 v[208:211], v155 offset:22528
	ds_read_b128 v[212:215], v155 offset:23552
	global_load_lds_dwordx4 v[148:149], off
	s_add_i32 m0, s16, 0x2000
	s_add_u32 s54, s30, 0xb0000
	v_lshl_add_u64 v[216:217], s[30:31], 0, v[134:135]
	s_addc_u32 s55, s31, 0
	s_add_i32 s16, s48, s33
	global_load_lds_dwordx4 v[216:217], off
	v_lshl_add_u64 v[218:219], s[54:55], 0, v[130:131]
	s_mov_b32 m0, s16
	v_lshl_add_u64 v[220:221], s[36:37], 0, v[132:133]
	global_load_lds_dwordx4 v[218:219], off
	v_lshl_add_u64 v[218:219], s[54:55], 0, v[134:135]
	s_add_i32 m0, s16, 0x2000
	s_nop 0
	global_load_lds_dwordx4 v[218:219], off
	v_lshl_add_u64 v[218:219], s[36:37], 0, v[128:129]
	s_mov_b32 m0, s39
	s_nop 0
	global_load_lds_dwordx4 v[218:219], off
	s_mov_b32 m0, s40
	s_nop 0
	global_load_lds_dwordx4 v[220:221], off
	s_waitcnt vmcnt(8)
	s_waitcnt lgkmcnt(0)
	s_barrier
	s_setprio 1
	s_waitcnt lgkmcnt(0)
	v_mfma_f32_16x16x32_bf16 v[60:63], v[144:147], v[184:187], 0
	v_mfma_f32_16x16x32_bf16 v[56:59], v[160:163], v[184:187], 0
	v_mfma_f32_16x16x32_bf16 v[52:55], v[144:147], v[192:195], 0
	v_mfma_f32_16x16x32_bf16 v[40:43], v[160:163], v[192:195], 0
	v_mfma_f32_16x16x32_bf16 v[36:39], v[144:147], v[200:203], 0
	v_mfma_f32_16x16x32_bf16 v[24:27], v[160:163], v[200:203], 0
	v_mfma_f32_16x16x32_bf16 v[20:23], v[144:147], v[208:211], 0
	v_mfma_f32_16x16x32_bf16 v[8:11], v[160:163], v[208:211], 0
	v_mfma_f32_16x16x32_bf16 v[60:63], v[156:159], v[188:191], v[60:63]
	v_mfma_f32_16x16x32_bf16 v[56:59], v[164:167], v[188:191], v[56:59]
	v_mfma_f32_16x16x32_bf16 v[52:55], v[156:159], v[196:199], v[52:55]
	v_mfma_f32_16x16x32_bf16 v[40:43], v[164:167], v[196:199], v[40:43]
	v_mfma_f32_16x16x32_bf16 v[36:39], v[156:159], v[204:207], v[36:39]
	v_mfma_f32_16x16x32_bf16 v[24:27], v[164:167], v[204:207], v[24:27]
	v_mfma_f32_16x16x32_bf16 v[20:23], v[156:159], v[212:215], v[20:23]
	v_mfma_f32_16x16x32_bf16 v[8:11], v[164:167], v[212:215], v[8:11]
	s_setprio 0
	s_setprio 1
	v_mfma_f32_16x16x32_bf16 v[48:51], v[168:171], v[184:187], 0
	v_mfma_f32_16x16x32_bf16 v[44:47], v[176:179], v[184:187], 0
	v_mfma_f32_16x16x32_bf16 v[32:35], v[168:171], v[192:195], 0
	v_mfma_f32_16x16x32_bf16 v[28:31], v[176:179], v[192:195], 0
	v_mfma_f32_16x16x32_bf16 v[16:19], v[168:171], v[200:203], 0
	v_mfma_f32_16x16x32_bf16 v[12:15], v[176:179], v[200:203], 0
	v_mfma_f32_16x16x32_bf16 v[4:7], v[168:171], v[208:211], 0
	v_mfma_f32_16x16x32_bf16 v[0:3], v[176:179], v[208:211], 0
	v_mfma_f32_16x16x32_bf16 v[48:51], v[172:175], v[188:191], v[48:51]
	v_mfma_f32_16x16x32_bf16 v[44:47], v[180:183], v[188:191], v[44:47]
	v_mfma_f32_16x16x32_bf16 v[32:35], v[172:175], v[196:199], v[32:35]
	v_mfma_f32_16x16x32_bf16 v[28:31], v[180:183], v[196:199], v[28:31]
	v_mfma_f32_16x16x32_bf16 v[16:19], v[172:175], v[204:207], v[16:19]
	v_mfma_f32_16x16x32_bf16 v[12:15], v[180:183], v[204:207], v[12:15]
	v_mfma_f32_16x16x32_bf16 v[4:7], v[172:175], v[212:215], v[4:7]
	v_mfma_f32_16x16x32_bf16 v[0:3], v[180:183], v[212:215], v[0:3]
	s_setprio 0
	s_barrier
	s_branch .Lpeelp7_mid

.Lpeelp7_mid:
	s_add_i32 s16, 0, 0x18000
	s_add_i32 s54, 0, 0x1c000
	v_add_u32_e32 v164, s16, v151
	v_add_u32_e32 v180, s54, v151
	ds_read_b128 v[144:147], v164
	ds_read_b128 v[156:159], v164 offset:1024
	ds_read_b128 v[160:163], v164 offset:2048
	ds_read_b128 v[164:167], v164 offset:3072
	ds_read_b128 v[168:171], v180
	ds_read_b128 v[172:175], v180 offset:1024
	ds_read_b128 v[176:179], v180 offset:2048
	ds_read_b128 v[180:183], v180 offset:3072
	s_add_u32 s36, s36, 0xb0000
	s_addc_u32 s37, s37, 0
	s_mov_b32 m0, s41
	v_lshl_add_u64 v[222:223], s[36:37], 0, v[128:129]
	ds_read_b128 v[184:187], v155 offset:32768
	ds_read_b128 v[188:191], v155 offset:33792
	ds_read_b128 v[192:195], v155 offset:34816
	ds_read_b128 v[196:199], v155 offset:35840
	ds_read_b128 v[200:203], v155 offset:36864
	ds_read_b128 v[204:207], v155 offset:37888
	ds_read_b128 v[208:211], v155 offset:38912
	ds_read_b128 v[212:215], v155 offset:39936
	global_load_lds_dwordx4 v[222:223], off
	v_lshl_add_u64 v[222:223], s[36:37], 0, v[132:133]
	s_mov_b32 m0, s42
	s_nop 0
	global_load_lds_dwordx4 v[222:223], off
	s_waitcnt vmcnt(8)
	s_waitcnt lgkmcnt(0)
	s_barrier
	s_setprio 1
	s_waitcnt lgkmcnt(0)
	v_mfma_f32_16x16x32_bf16 v[124:127], v[144:147], v[184:187], v[124:127]
	v_mfma_f32_16x16x32_bf16 v[120:123], v[160:163], v[184:187], v[120:123]
	v_mfma_f32_16x16x32_bf16 v[116:119], v[144:147], v[192:195], v[116:119]
	v_mfma_f32_16x16x32_bf16 v[104:107], v[160:163], v[192:195], v[104:107]
	v_mfma_f32_16x16x32_bf16 v[100:103], v[144:147], v[200:203], v[100:103]
	v_mfma_f32_16x16x32_bf16 v[88:91], v[160:163], v[200:203], v[88:91]
	v_mfma_f32_16x16x32_bf16 v[84:87], v[144:147], v[208:211], v[84:87]
	v_mfma_f32_16x16x32_bf16 v[72:75], v[160:163], v[208:211], v[72:75]
	v_mfma_f32_16x16x32_bf16 v[124:127], v[156:159], v[188:191], v[124:127]
	v_mfma_f32_16x16x32_bf16 v[120:123], v[164:167], v[188:191], v[120:123]
	v_mfma_f32_16x16x32_bf16 v[116:119], v[156:159], v[196:199], v[116:119]
	v_mfma_f32_16x16x32_bf16 v[104:107], v[164:167], v[196:199], v[104:107]
	v_mfma_f32_16x16x32_bf16 v[100:103], v[156:159], v[204:207], v[100:103]
	v_mfma_f32_16x16x32_bf16 v[88:91], v[164:167], v[204:207], v[88:91]
	v_mfma_f32_16x16x32_bf16 v[84:87], v[156:159], v[212:215], v[84:87]
	v_mfma_f32_16x16x32_bf16 v[72:75], v[164:167], v[212:215], v[72:75]
	s_setprio 0
	s_setprio 1
	v_mfma_f32_16x16x32_bf16 v[112:115], v[168:171], v[184:187], v[112:115]
	v_mfma_f32_16x16x32_bf16 v[108:111], v[176:179], v[184:187], v[108:111]
	v_mfma_f32_16x16x32_bf16 v[96:99], v[168:171], v[192:195], v[96:99]
	v_mfma_f32_16x16x32_bf16 v[92:95], v[176:179], v[192:195], v[92:95]
	v_mfma_f32_16x16x32_bf16 v[80:83], v[168:171], v[200:203], v[80:83]
	v_mfma_f32_16x16x32_bf16 v[76:79], v[176:179], v[200:203], v[76:79]
	v_mfma_f32_16x16x32_bf16 v[68:71], v[168:171], v[208:211], v[68:71]
	v_mfma_f32_16x16x32_bf16 v[64:67], v[176:179], v[208:211], v[64:67]
	v_mfma_f32_16x16x32_bf16 v[112:115], v[172:175], v[188:191], v[112:115]
	v_mfma_f32_16x16x32_bf16 v[108:111], v[180:183], v[188:191], v[108:111]
	v_mfma_f32_16x16x32_bf16 v[96:99], v[172:175], v[196:199], v[96:99]
	v_mfma_f32_16x16x32_bf16 v[92:95], v[180:183], v[196:199], v[92:95]
	v_mfma_f32_16x16x32_bf16 v[80:83], v[172:175], v[204:207], v[80:83]
	v_mfma_f32_16x16x32_bf16 v[76:79], v[180:183], v[204:207], v[76:79]
	v_mfma_f32_16x16x32_bf16 v[68:71], v[172:175], v[212:215], v[68:71]
	v_mfma_f32_16x16x32_bf16 v[64:67], v[180:183], v[212:215], v[64:67]
	s_setprio 0
	s_barrier
	s_add_i32 s16, s16, s33
	v_lshl_add_u64 v[148:149], v[148:149], 0, s[8:9]
	s_mov_b32 m0, s16
	ds_read_b128 v[184:187], v155 offset:49152
	ds_read_b128 v[188:191], v155 offset:50176
	ds_read_b128 v[192:195], v155 offset:51200
	ds_read_b128 v[196:199], v155 offset:52224
	ds_read_b128 v[200:203], v155 offset:53248
	ds_read_b128 v[204:207], v155 offset:54272
	ds_read_b128 v[208:211], v155 offset:55296
	ds_read_b128 v[212:215], v155 offset:56320
	global_load_lds_dwordx4 v[148:149], off
	s_add_i32 m0, s16, 0x2000
	s_add_u32 s30, s30, 0xb0080
	v_lshl_add_u64 v[148:149], v[216:217], 0, s[8:9]
	s_addc_u32 s31, s31, 0
	s_add_i32 s16, s54, s33
	global_load_lds_dwordx4 v[148:149], off
	v_lshl_add_u64 v[148:149], s[30:31], 0, v[130:131]
	s_mov_b32 m0, s16
	s_nop 0
	global_load_lds_dwordx4 v[148:149], off
	v_lshl_add_u64 v[148:149], s[30:31], 0, v[134:135]
	s_add_i32 m0, s16, 0x2000
	s_nop 0
	global_load_lds_dwordx4 v[148:149], off
	v_lshl_add_u64 v[148:149], v[218:219], 0, s[8:9]
	s_mov_b32 m0, s45
	s_nop 0
	global_load_lds_dwordx4 v[148:149], off
	v_lshl_add_u64 v[148:149], v[220:221], 0, s[8:9]
	s_mov_b32 m0, s46
	s_nop 0
	global_load_lds_dwordx4 v[148:149], off
	s_waitcnt vmcnt(8)
	s_waitcnt lgkmcnt(0)
	s_barrier
	s_setprio 1
	s_waitcnt lgkmcnt(0)
	v_mfma_f32_16x16x32_bf16 v[60:63], v[144:147], v[184:187], v[60:63]
	v_mfma_f32_16x16x32_bf16 v[56:59], v[160:163], v[184:187], v[56:59]
	v_mfma_f32_16x16x32_bf16 v[52:55], v[144:147], v[192:195], v[52:55]
	v_mfma_f32_16x16x32_bf16 v[40:43], v[160:163], v[192:195], v[40:43]
	v_mfma_f32_16x16x32_bf16 v[36:39], v[144:147], v[200:203], v[36:39]
	v_mfma_f32_16x16x32_bf16 v[24:27], v[160:163], v[200:203], v[24:27]
	v_mfma_f32_16x16x32_bf16 v[20:23], v[144:147], v[208:211], v[20:23]
	v_mfma_f32_16x16x32_bf16 v[8:11], v[160:163], v[208:211], v[8:11]
	v_mfma_f32_16x16x32_bf16 v[60:63], v[156:159], v[188:191], v[60:63]
	v_mfma_f32_16x16x32_bf16 v[56:59], v[164:167], v[188:191], v[56:59]
	v_mfma_f32_16x16x32_bf16 v[52:55], v[156:159], v[196:199], v[52:55]
	v_mfma_f32_16x16x32_bf16 v[40:43], v[164:167], v[196:199], v[40:43]
	v_mfma_f32_16x16x32_bf16 v[36:39], v[156:159], v[204:207], v[36:39]
	v_mfma_f32_16x16x32_bf16 v[24:27], v[164:167], v[204:207], v[24:27]
	v_mfma_f32_16x16x32_bf16 v[20:23], v[156:159], v[212:215], v[20:23]
	v_mfma_f32_16x16x32_bf16 v[8:11], v[164:167], v[212:215], v[8:11]
	s_setprio 0
	s_setprio 1
	v_mfma_f32_16x16x32_bf16 v[48:51], v[168:171], v[184:187], v[48:51]
	v_mfma_f32_16x16x32_bf16 v[44:47], v[176:179], v[184:187], v[44:47]
	v_mfma_f32_16x16x32_bf16 v[32:35], v[168:171], v[192:195], v[32:35]
	v_mfma_f32_16x16x32_bf16 v[28:31], v[176:179], v[192:195], v[28:31]
	v_mfma_f32_16x16x32_bf16 v[16:19], v[168:171], v[200:203], v[16:19]
	v_mfma_f32_16x16x32_bf16 v[12:15], v[176:179], v[200:203], v[12:15]
	v_mfma_f32_16x16x32_bf16 v[4:7], v[168:171], v[208:211], v[4:7]
	v_mfma_f32_16x16x32_bf16 v[0:3], v[176:179], v[208:211], v[0:3]
	v_mfma_f32_16x16x32_bf16 v[48:51], v[172:175], v[188:191], v[48:51]
	v_mfma_f32_16x16x32_bf16 v[44:47], v[180:183], v[188:191], v[44:47]
	v_mfma_f32_16x16x32_bf16 v[32:35], v[172:175], v[196:199], v[32:35]
	v_mfma_f32_16x16x32_bf16 v[28:31], v[180:183], v[196:199], v[28:31]
	v_mfma_f32_16x16x32_bf16 v[16:19], v[172:175], v[204:207], v[16:19]
	v_mfma_f32_16x16x32_bf16 v[12:15], v[180:183], v[204:207], v[12:15]
	v_mfma_f32_16x16x32_bf16 v[4:7], v[172:175], v[212:215], v[4:7]
	v_mfma_f32_16x16x32_bf16 v[0:3], v[180:183], v[212:215], v[0:3]
	s_setprio 0
	s_barrier
	s_add_i32 s53, s53, 2
	s_add_u32 s28, s28, 0x100
	s_addc_u32 s29, s29, 0
	s_add_u32 s51, s51, 0x100
	s_addc_u32 s52, s52, 0
	s_cmp_gt_u32 s53, 41
	s_cbranch_scc0 .LBB0_762
	s_and_b64 vcc, exec, s[10:11]
	s_cbranch_vccz .LBB0_765
	s_barrier
